# P4 chunk sections: B-operand global loads of all 4 k-steps issued early into spare VGPRs (v240-255), counted vmcnt waits instead of full drains
# baseline (speedup 1.0000x reference)
.LBB0_738:
	s_waitcnt lgkmcnt(0)
	ds_read_b32 v8, v202 offset:4
	s_waitcnt vmcnt(0)
	v_lshlrev_b32_e32 v12, 16, v4
	v_and_b32_e32 v13, 0xffff0000, v4
	v_or_b32_e32 v16, s24, v141
	s_mov_b32 s30, 0x20000
	s_waitcnt lgkmcnt(0)
	v_pk_mul_f32 v[12:13], v[8:9], v[12:13] op_sel_hi:[0,1]
	v_cvt_pk_bf16_f32 v4, v12, v13
	v_lshlrev_b32_e32 v12, 16, v5
	v_and_b32_e32 v13, 0xffff0000, v5
	v_pk_mul_f32 v[12:13], v[8:9], v[12:13] op_sel_hi:[0,1]
	v_cvt_pk_bf16_f32 v5, v12, v13
	v_lshlrev_b32_e32 v12, 16, v6
	v_and_b32_e32 v13, 0xffff0000, v6
	v_pk_mul_f32 v[12:13], v[8:9], v[12:13] op_sel_hi:[0,1]
	v_cvt_pk_bf16_f32 v6, v12, v13
	v_lshlrev_b32_e32 v12, 16, v7
	v_and_b32_e32 v13, 0xffff0000, v7
	v_pk_mul_f32 v[8:9], v[8:9], v[12:13] op_sel_hi:[0,1]
	v_cvt_pk_bf16_f32 v7, v8, v9
	ds_write_b128 v85, v[4:7] offset:26112
	flat_load_dwordx4 v[4:7], v[10:11]
	ds_read_b32 v8, v203 offset:4
	s_waitcnt vmcnt(0) lgkmcnt(0)
	v_lshlrev_b32_e32 v10, 16, v4
	v_and_b32_e32 v11, 0xffff0000, v4
	v_pk_mul_f32 v[10:11], v[8:9], v[10:11] op_sel_hi:[0,1]
	v_cvt_pk_bf16_f32 v4, v10, v11
	v_lshlrev_b32_e32 v10, 16, v5
	v_and_b32_e32 v11, 0xffff0000, v5
	v_pk_mul_f32 v[10:11], v[8:9], v[10:11] op_sel_hi:[0,1]
	v_cvt_pk_bf16_f32 v5, v10, v11
	v_lshlrev_b32_e32 v10, 16, v6
	v_and_b32_e32 v11, 0xffff0000, v6
	v_pk_mul_f32 v[10:11], v[8:9], v[10:11] op_sel_hi:[0,1]
	v_cvt_pk_bf16_f32 v6, v10, v11
	v_lshlrev_b32_e32 v10, 16, v7
	v_and_b32_e32 v11, 0xffff0000, v7
	v_pk_mul_f32 v[8:9], v[8:9], v[10:11] op_sel_hi:[0,1]
	v_cvt_pk_bf16_f32 v7, v8, v9
	ds_write_b128 v85, v[4:7] offset:30464
	v_or_b32_e32 v4, v16, v216
	v_ashrrev_i32_e32 v5, 31, v4
	v_lshlrev_b64 v[4:5], 13, v[4:5]
	v_lshl_add_u64 v[12:13], v[112:113], 0, v[4:5]
	v_add_co_u32_e32 v14, vcc, s30, v12
	s_waitcnt lgkmcnt(0)
	s_nop 0
	v_addc_co_u32_e32 v15, vcc, 0, v13, vcc
	s_barrier
	global_load_dwordx4 v[4:7], v[12:13], off
	global_load_dwordx4 v[8:11], v[14:15], off
	global_load_dwordx4 v[240:243], v[12:13], off offset:64
	global_load_dwordx4 v[244:247], v[14:15], off offset:64
	global_load_dwordx4 v[248:251], v[12:13], off offset:128
	global_load_dwordx4 v[252:255], v[14:15], off offset:128
	ds_read_b128 v[18:21], v204 offset:34816
	ds_read_b128 v[26:29], v204 offset:39168
	ds_read_b128 v[34:37], v204 offset:43520
	ds_read_b128 v[42:45], v204 offset:47872
	ds_read_b128 v[50:53], v204 offset:52224
	ds_read_b128 v[58:61], v204 offset:56576
	ds_read_b128 v[136:139], v204 offset:60928
	ds_read_b128 v[222:225], v204 offset:65280
	s_mov_b64 s[30:31], 0
	s_waitcnt vmcnt(4) lgkmcnt(0)
	v_mfma_f32_16x16x32_bf16 v[22:25], v[18:21], v[4:7], 0
	v_mfma_f32_16x16x32_bf16 v[18:21], v[18:21], v[8:11], 0
	v_mfma_f32_16x16x32_bf16 v[30:33], v[26:29], v[4:7], 0
	v_mfma_f32_16x16x32_bf16 v[26:29], v[26:29], v[8:11], 0
	v_mfma_f32_16x16x32_bf16 v[38:41], v[34:37], v[4:7], 0
	v_mfma_f32_16x16x32_bf16 v[34:37], v[34:37], v[8:11], 0
	v_mfma_f32_16x16x32_bf16 v[46:49], v[42:45], v[4:7], 0
	v_mfma_f32_16x16x32_bf16 v[42:45], v[42:45], v[8:11], 0
	v_mfma_f32_16x16x32_bf16 v[54:57], v[50:53], v[4:7], 0
	v_mfma_f32_16x16x32_bf16 v[50:53], v[50:53], v[8:11], 0
	v_mfma_f32_16x16x32_bf16 v[62:65], v[58:61], v[4:7], 0
	v_mfma_f32_16x16x32_bf16 v[58:61], v[58:61], v[8:11], 0
	v_mfma_f32_16x16x32_bf16 v[218:221], v[136:139], v[4:7], 0
	v_mfma_f32_16x16x32_bf16 v[136:139], v[136:139], v[8:11], 0
	v_mfma_f32_16x16x32_bf16 v[4:7], v[222:225], v[4:7], 0
	v_mfma_f32_16x16x32_bf16 v[8:11], v[222:225], v[8:11], 0
	ds_read_b128 v[230:233], v204 offset:34880
	s_waitcnt vmcnt(2) lgkmcnt(0)
	v_mfma_f32_16x16x32_bf16 v[22:25], v[230:233], v[240:243], v[22:25]
	v_mfma_f32_16x16x32_bf16 v[18:21], v[230:233], v[244:247], v[18:21]
	ds_read_b128 v[230:233], v204 offset:39232
	s_waitcnt lgkmcnt(0)
	v_mfma_f32_16x16x32_bf16 v[30:33], v[230:233], v[240:243], v[30:33]
	v_mfma_f32_16x16x32_bf16 v[26:29], v[230:233], v[244:247], v[26:29]
	ds_read_b128 v[230:233], v204 offset:43584
	s_waitcnt lgkmcnt(0)
	v_mfma_f32_16x16x32_bf16 v[38:41], v[230:233], v[240:243], v[38:41]
	v_mfma_f32_16x16x32_bf16 v[34:37], v[230:233], v[244:247], v[34:37]
	ds_read_b128 v[230:233], v204 offset:47936
	s_waitcnt lgkmcnt(0)
	v_mfma_f32_16x16x32_bf16 v[46:49], v[230:233], v[240:243], v[46:49]
	v_mfma_f32_16x16x32_bf16 v[42:45], v[230:233], v[244:247], v[42:45]
	ds_read_b128 v[230:233], v204 offset:52288
	s_waitcnt lgkmcnt(0)
	v_mfma_f32_16x16x32_bf16 v[54:57], v[230:233], v[240:243], v[54:57]
	v_mfma_f32_16x16x32_bf16 v[50:53], v[230:233], v[244:247], v[50:53]
	ds_read_b128 v[230:233], v204 offset:56640
	s_waitcnt lgkmcnt(0)
	v_mfma_f32_16x16x32_bf16 v[62:65], v[230:233], v[240:243], v[62:65]
	v_mfma_f32_16x16x32_bf16 v[58:61], v[230:233], v[244:247], v[58:61]
	ds_read_b128 v[230:233], v204 offset:60992
	s_waitcnt lgkmcnt(0)
	v_mfma_f32_16x16x32_bf16 v[218:221], v[230:233], v[240:243], v[218:221]
	v_mfma_f32_16x16x32_bf16 v[136:139], v[230:233], v[244:247], v[136:139]
	ds_read_b128 v[230:233], v204 offset:65344
	s_waitcnt lgkmcnt(0)
	v_mfma_f32_16x16x32_bf16 v[4:7], v[230:233], v[240:243], v[4:7]
	v_mfma_f32_16x16x32_bf16 v[8:11], v[230:233], v[244:247], v[8:11]
	global_load_dwordx4 v[240:243], v[12:13], off offset:192
	global_load_dwordx4 v[244:247], v[14:15], off offset:192
	ds_read_b128 v[230:233], v204 offset:34944
	s_waitcnt vmcnt(2) lgkmcnt(0)
	v_mfma_f32_16x16x32_bf16 v[22:25], v[230:233], v[248:251], v[22:25]
	v_mfma_f32_16x16x32_bf16 v[18:21], v[230:233], v[252:255], v[18:21]
	ds_read_b128 v[230:233], v204 offset:39296
	s_waitcnt lgkmcnt(0)
	v_mfma_f32_16x16x32_bf16 v[30:33], v[230:233], v[248:251], v[30:33]
	v_mfma_f32_16x16x32_bf16 v[26:29], v[230:233], v[252:255], v[26:29]
	ds_read_b128 v[230:233], v204 offset:43648
	s_waitcnt lgkmcnt(0)
	v_mfma_f32_16x16x32_bf16 v[38:41], v[230:233], v[248:251], v[38:41]
	v_mfma_f32_16x16x32_bf16 v[34:37], v[230:233], v[252:255], v[34:37]
	ds_read_b128 v[230:233], v204 offset:48000
	s_waitcnt lgkmcnt(0)
	v_mfma_f32_16x16x32_bf16 v[46:49], v[230:233], v[248:251], v[46:49]
	v_mfma_f32_16x16x32_bf16 v[42:45], v[230:233], v[252:255], v[42:45]
	ds_read_b128 v[230:233], v204 offset:52352
	s_waitcnt lgkmcnt(0)
	v_mfma_f32_16x16x32_bf16 v[54:57], v[230:233], v[248:251], v[54:57]
	v_mfma_f32_16x16x32_bf16 v[50:53], v[230:233], v[252:255], v[50:53]
	ds_read_b128 v[230:233], v204 offset:56704
	s_waitcnt lgkmcnt(0)
	v_mfma_f32_16x16x32_bf16 v[62:65], v[230:233], v[248:251], v[62:65]
	v_mfma_f32_16x16x32_bf16 v[58:61], v[230:233], v[252:255], v[58:61]
	ds_read_b128 v[230:233], v204 offset:61056
	s_waitcnt lgkmcnt(0)
	v_mfma_f32_16x16x32_bf16 v[218:221], v[230:233], v[248:251], v[218:221]
	v_mfma_f32_16x16x32_bf16 v[136:139], v[230:233], v[252:255], v[136:139]
	ds_read_b128 v[230:233], v204 offset:65408
	s_waitcnt lgkmcnt(0)
	v_mfma_f32_16x16x32_bf16 v[4:7], v[230:233], v[248:251], v[4:7]
	s_nop 0
	v_mfma_f32_16x16x32_bf16 v[8:11], v[230:233], v[252:255], v[8:11]
	ds_read_b128 v[226:229], v204 offset:35008
	ds_read_b128 v[230:233], v204
	s_waitcnt vmcnt(0) lgkmcnt(0)
	v_mfma_f32_16x16x32_bf16 v[22:25], v[226:229], v[240:243], v[22:25]
	v_mfma_f32_16x16x32_bf16 v[18:21], v[226:229], v[244:247], v[18:21]
	ds_read_b128 v[226:229], v204 offset:39360
	s_waitcnt lgkmcnt(0)
	v_mfma_f32_16x16x32_bf16 v[30:33], v[226:229], v[240:243], v[30:33]
	v_mfma_f32_16x16x32_bf16 v[26:29], v[226:229], v[244:247], v[26:29]
	ds_read_b128 v[226:229], v204 offset:43712
	s_waitcnt lgkmcnt(0)
	v_mfma_f32_16x16x32_bf16 v[38:41], v[226:229], v[240:243], v[38:41]
	v_mfma_f32_16x16x32_bf16 v[34:37], v[226:229], v[244:247], v[34:37]
	ds_read_b128 v[226:229], v204 offset:48064
	s_waitcnt lgkmcnt(0)
	v_mfma_f32_16x16x32_bf16 v[46:49], v[226:229], v[240:243], v[46:49]
	v_mfma_f32_16x16x32_bf16 v[42:45], v[226:229], v[244:247], v[42:45]
	ds_read_b128 v[226:229], v204 offset:52416
	s_waitcnt lgkmcnt(0)
	v_mfma_f32_16x16x32_bf16 v[54:57], v[226:229], v[240:243], v[54:57]
	v_mfma_f32_16x16x32_bf16 v[50:53], v[226:229], v[244:247], v[50:53]
	ds_read_b128 v[226:229], v204 offset:56768
	s_waitcnt lgkmcnt(0)
	v_mfma_f32_16x16x32_bf16 v[62:65], v[226:229], v[240:243], v[62:65]
	v_mfma_f32_16x16x32_bf16 v[58:61], v[226:229], v[244:247], v[58:61]
	ds_read_b128 v[226:229], v204 offset:61120
	s_waitcnt lgkmcnt(0)
	v_mfma_f32_16x16x32_bf16 v[218:221], v[226:229], v[240:243], v[218:221]
	v_mfma_f32_16x16x32_bf16 v[136:139], v[226:229], v[244:247], v[136:139]
	ds_read_b128 v[226:229], v204 offset:65472
	s_waitcnt lgkmcnt(0)
	v_mfma_f32_16x16x32_bf16 v[222:225], v[226:229], v[240:243], v[4:7]
	s_nop 2
	v_or_b32_e32 v4, v16, v73
	v_lshlrev_b32_e32 v68, 8, v4
	v_lshl_add_u64 v[6:7], v[0:1], 0, v[68:69]
	v_add_co_u32_e32 v4, vcc, s37, v6
	v_mfma_f32_16x16x32_bf16 v[8:11], v[226:229], v[244:247], v[8:11]
	s_nop 0
	v_addc_co_u32_e32 v5, vcc, 0, v7, vcc
	global_load_dwordx4 v[12:15], v[6:7], off
	global_load_dwordx4 v[226:229], v[4:5], off
	global_load_dwordx4 v[240:243], v[6:7], off offset:64
	global_load_dwordx4 v[244:247], v[4:5], off offset:64
	global_load_dwordx4 v[248:251], v[6:7], off offset:128
	global_load_dwordx4 v[252:255], v[4:5], off offset:128
	s_waitcnt vmcnt(4) lgkmcnt(0)
	v_mfma_f32_16x16x32_bf16 v[22:25], v[230:233], v[12:15], v[22:25]
	v_mfma_f32_16x16x32_bf16 v[16:19], v[230:233], v[226:229], v[18:21]
	ds_read_b128 v[230:233], v204 offset:4352
	s_waitcnt lgkmcnt(0)
	v_mfma_f32_16x16x32_bf16 v[30:33], v[230:233], v[12:15], v[30:33]
	v_mfma_f32_16x16x32_bf16 v[26:29], v[230:233], v[226:229], v[26:29]
	ds_read_b128 v[230:233], v204 offset:8704
	s_waitcnt lgkmcnt(0)
	v_mfma_f32_16x16x32_bf16 v[38:41], v[230:233], v[12:15], v[38:41]
	v_mfma_f32_16x16x32_bf16 v[34:37], v[230:233], v[226:229], v[34:37]
	ds_read_b128 v[230:233], v204 offset:13056
	s_waitcnt lgkmcnt(0)
	v_mfma_f32_16x16x32_bf16 v[46:49], v[230:233], v[12:15], v[46:49]
	v_mfma_f32_16x16x32_bf16 v[42:45], v[230:233], v[226:229], v[42:45]
	ds_read_b128 v[230:233], v204 offset:17408
	s_waitcnt lgkmcnt(0)
	v_mfma_f32_16x16x32_bf16 v[54:57], v[230:233], v[12:15], v[54:57]
	v_mfma_f32_16x16x32_bf16 v[50:53], v[230:233], v[226:229], v[50:53]
	ds_read_b128 v[230:233], v204 offset:21760
	s_waitcnt lgkmcnt(0)
	v_mfma_f32_16x16x32_bf16 v[62:65], v[230:233], v[12:15], v[62:65]
	v_mfma_f32_16x16x32_bf16 v[58:61], v[230:233], v[226:229], v[58:61]
	ds_read_b128 v[230:233], v204 offset:26112
	s_waitcnt lgkmcnt(0)
	v_mfma_f32_16x16x32_bf16 v[218:221], v[230:233], v[12:15], v[218:221]
	v_mfma_f32_16x16x32_bf16 v[136:139], v[230:233], v[226:229], v[136:139]
	ds_read_b128 v[230:233], v204 offset:30464
	s_waitcnt lgkmcnt(0)
	v_mfma_f32_16x16x32_bf16 v[12:15], v[230:233], v[12:15], v[222:225]
	v_mfma_f32_16x16x32_bf16 v[8:11], v[230:233], v[226:229], v[8:11]
	s_nop 1
	ds_read_b128 v[230:233], v204 offset:64
	s_waitcnt vmcnt(2) lgkmcnt(0)
	v_mfma_f32_16x16x32_bf16 v[20:23], v[230:233], v[240:243], v[22:25]
	v_mfma_f32_16x16x32_bf16 v[16:19], v[230:233], v[244:247], v[16:19]
	ds_read_b128 v[230:233], v204 offset:4416
	s_waitcnt lgkmcnt(0)
	v_mfma_f32_16x16x32_bf16 v[30:33], v[230:233], v[240:243], v[30:33]
	v_mfma_f32_16x16x32_bf16 v[24:27], v[230:233], v[244:247], v[26:29]
	ds_read_b128 v[230:233], v204 offset:8768
	s_waitcnt lgkmcnt(0)
	v_mfma_f32_16x16x32_bf16 v[38:41], v[230:233], v[240:243], v[38:41]
	v_mfma_f32_16x16x32_bf16 v[34:37], v[230:233], v[244:247], v[34:37]
	ds_read_b128 v[230:233], v204 offset:13120
	s_waitcnt lgkmcnt(0)
	v_mfma_f32_16x16x32_bf16 v[46:49], v[230:233], v[240:243], v[46:49]
	v_mfma_f32_16x16x32_bf16 v[42:45], v[230:233], v[244:247], v[42:45]
	ds_read_b128 v[230:233], v204 offset:17472
	s_waitcnt lgkmcnt(0)
	v_mfma_f32_16x16x32_bf16 v[54:57], v[230:233], v[240:243], v[54:57]
	v_mfma_f32_16x16x32_bf16 v[50:53], v[230:233], v[244:247], v[50:53]
	ds_read_b128 v[230:233], v204 offset:21824
	s_waitcnt lgkmcnt(0)
	v_mfma_f32_16x16x32_bf16 v[62:65], v[230:233], v[240:243], v[62:65]
	v_mfma_f32_16x16x32_bf16 v[58:61], v[230:233], v[244:247], v[58:61]
	ds_read_b128 v[230:233], v204 offset:26176
	s_waitcnt lgkmcnt(0)
	v_mfma_f32_16x16x32_bf16 v[218:221], v[230:233], v[240:243], v[218:221]
	v_mfma_f32_16x16x32_bf16 v[136:139], v[230:233], v[244:247], v[136:139]
	ds_read_b128 v[230:233], v204 offset:30528
	s_waitcnt lgkmcnt(0)
	v_mfma_f32_16x16x32_bf16 v[12:15], v[230:233], v[240:243], v[12:15]
	v_mfma_f32_16x16x32_bf16 v[8:11], v[230:233], v[244:247], v[8:11]
	global_load_dwordx4 v[240:243], v[6:7], off offset:192
	global_load_dwordx4 v[244:247], v[4:5], off offset:192
	ds_read_b128 v[230:233], v204 offset:128
	s_waitcnt vmcnt(2) lgkmcnt(0)
	v_mfma_f32_16x16x32_bf16 v[20:23], v[230:233], v[248:251], v[20:23]
	v_mfma_f32_16x16x32_bf16 v[16:19], v[230:233], v[252:255], v[16:19]
	ds_read_b128 v[230:233], v204 offset:4480
	s_waitcnt lgkmcnt(0)
	v_mfma_f32_16x16x32_bf16 v[28:31], v[230:233], v[248:251], v[30:33]
	v_mfma_f32_16x16x32_bf16 v[24:27], v[230:233], v[252:255], v[24:27]
	ds_read_b128 v[230:233], v204 offset:8832
	s_waitcnt lgkmcnt(0)
	v_mfma_f32_16x16x32_bf16 v[38:41], v[230:233], v[248:251], v[38:41]
	v_mfma_f32_16x16x32_bf16 v[32:35], v[230:233], v[252:255], v[34:37]
	ds_read_b128 v[230:233], v204 offset:13184
	s_waitcnt lgkmcnt(0)
	v_mfma_f32_16x16x32_bf16 v[46:49], v[230:233], v[248:251], v[46:49]
	v_mfma_f32_16x16x32_bf16 v[42:45], v[230:233], v[252:255], v[42:45]
	ds_read_b128 v[230:233], v204 offset:17536
	s_waitcnt lgkmcnt(0)
	v_mfma_f32_16x16x32_bf16 v[54:57], v[230:233], v[248:251], v[54:57]
	v_mfma_f32_16x16x32_bf16 v[50:53], v[230:233], v[252:255], v[50:53]
	ds_read_b128 v[230:233], v204 offset:21888
	s_waitcnt lgkmcnt(0)
	v_mfma_f32_16x16x32_bf16 v[62:65], v[230:233], v[248:251], v[62:65]
	v_mfma_f32_16x16x32_bf16 v[58:61], v[230:233], v[252:255], v[58:61]
	ds_read_b128 v[230:233], v204 offset:26240
	s_waitcnt lgkmcnt(0)
	v_mfma_f32_16x16x32_bf16 v[218:221], v[230:233], v[248:251], v[218:221]
	v_mfma_f32_16x16x32_bf16 v[136:139], v[230:233], v[252:255], v[136:139]
	ds_read_b128 v[230:233], v204 offset:30592
	s_waitcnt lgkmcnt(0)
	v_mfma_f32_16x16x32_bf16 v[222:225], v[230:233], v[248:251], v[12:15]
	v_mfma_f32_16x16x32_bf16 v[226:229], v[230:233], v[252:255], v[8:11]
	s_nop 0
	ds_read_b128 v[8:11], v204 offset:192
	s_waitcnt vmcnt(0) lgkmcnt(0)
	v_mfma_f32_16x16x32_bf16 v[4:7], v[8:11], v[240:243], v[20:23]
	v_mfma_f32_16x16x32_bf16 v[8:11], v[8:11], v[244:247], v[16:19]
	s_nop 2
	ds_read_b128 v[16:19], v204 offset:4544
	s_waitcnt lgkmcnt(0)
	v_mfma_f32_16x16x32_bf16 v[12:15], v[16:19], v[240:243], v[28:31]
	v_mfma_f32_16x16x32_bf16 v[16:19], v[16:19], v[244:247], v[24:27]
	s_nop 2
	ds_read_b128 v[24:27], v204 offset:8896
	s_waitcnt lgkmcnt(0)
	v_mfma_f32_16x16x32_bf16 v[20:23], v[24:27], v[240:243], v[38:41]
	v_mfma_f32_16x16x32_bf16 v[24:27], v[24:27], v[244:247], v[32:35]
	s_nop 2
	ds_read_b128 v[32:35], v204 offset:13248
	s_waitcnt lgkmcnt(0)
	v_mfma_f32_16x16x32_bf16 v[28:31], v[32:35], v[240:243], v[46:49]
	v_mfma_f32_16x16x32_bf16 v[32:35], v[32:35], v[244:247], v[42:45]
	s_nop 2
	ds_read_b128 v[40:43], v204 offset:17600
	s_waitcnt lgkmcnt(0)
	v_mfma_f32_16x16x32_bf16 v[36:39], v[40:43], v[240:243], v[54:57]
	v_mfma_f32_16x16x32_bf16 v[40:43], v[40:43], v[244:247], v[50:53]
	s_nop 2
	ds_read_b128 v[48:51], v204 offset:21952
	s_waitcnt lgkmcnt(0)
	v_mfma_f32_16x16x32_bf16 v[44:47], v[48:51], v[240:243], v[62:65]
	s_nop 2
	ds_read_b128 v[64:67], v204 offset:30656
	v_mfma_f32_16x16x32_bf16 v[48:51], v[48:51], v[244:247], v[58:61]
	s_nop 2
	ds_read_b128 v[56:59], v204 offset:26304
	s_waitcnt lgkmcnt(0)
	v_mfma_f32_16x16x32_bf16 v[52:55], v[56:59], v[240:243], v[218:221]
	s_barrier
	v_mfma_f32_16x16x32_bf16 v[56:59], v[56:59], v[244:247], v[136:139]
	s_nop 2
	ds_read_b128 v[136:139], v85
	ds_read_b32 v91, v180
	ds_read_b32 v93, v181 offset:4
	s_waitcnt lgkmcnt(2)
	v_lshlrev_b32_e32 v220, 16, v136
	v_and_b32_e32 v221, 0xffff0000, v136
	s_waitcnt lgkmcnt(0)
	v_mul_f32_e32 v218, v91, v93
	v_pk_mul_f32 v[220:221], v[218:219], v[220:221] op_sel_hi:[0,1]
	v_cvt_pk_bf16_f32 v136, v220, v221
	v_lshlrev_b32_e32 v220, 16, v137
	v_and_b32_e32 v221, 0xffff0000, v137
	v_pk_mul_f32 v[220:221], v[218:219], v[220:221] op_sel_hi:[0,1]
	v_cvt_pk_bf16_f32 v137, v220, v221
	v_lshlrev_b32_e32 v220, 16, v138
	v_and_b32_e32 v221, 0xffff0000, v138
	v_pk_mul_f32 v[220:221], v[218:219], v[220:221] op_sel_hi:[0,1]
	v_cvt_pk_bf16_f32 v138, v220, v221
	v_lshlrev_b32_e32 v220, 16, v139
	v_and_b32_e32 v221, 0xffff0000, v139
	v_pk_mul_f32 v[218:219], v[218:219], v[220:221] op_sel_hi:[0,1]
	v_cvt_pk_bf16_f32 v139, v218, v219
	ds_write_b128 v85, v[136:139]
	ds_read_b128 v[136:139], v85 offset:4352
	ds_read_b32 v91, v182
	ds_read_b32 v93, v183 offset:4
	v_mfma_f32_16x16x32_bf16 v[60:63], v[64:67], v[240:243], v[222:225]
	s_waitcnt lgkmcnt(2)
	v_lshlrev_b32_e32 v220, 16, v136
	v_and_b32_e32 v221, 0xffff0000, v136
	s_waitcnt lgkmcnt(0)
	v_mul_f32_e32 v218, v91, v93
	v_pk_mul_f32 v[220:221], v[218:219], v[220:221] op_sel_hi:[0,1]
	v_cvt_pk_bf16_f32 v136, v220, v221
	v_lshlrev_b32_e32 v220, 16, v137
	v_and_b32_e32 v221, 0xffff0000, v137
	v_pk_mul_f32 v[220:221], v[218:219], v[220:221] op_sel_hi:[0,1]
	v_cvt_pk_bf16_f32 v137, v220, v221
	v_lshlrev_b32_e32 v220, 16, v138
	v_and_b32_e32 v221, 0xffff0000, v138
	v_pk_mul_f32 v[220:221], v[218:219], v[220:221] op_sel_hi:[0,1]
	v_cvt_pk_bf16_f32 v138, v220, v221
	v_lshlrev_b32_e32 v220, 16, v139
	v_and_b32_e32 v221, 0xffff0000, v139
	v_pk_mul_f32 v[218:219], v[218:219], v[220:221] op_sel_hi:[0,1]
	v_cvt_pk_bf16_f32 v139, v218, v219
	ds_write_b128 v85, v[136:139] offset:4352
	ds_read_b128 v[136:139], v85 offset:8704
	ds_read_b32 v91, v184
	ds_read_b32 v93, v185 offset:4
	v_mfma_f32_16x16x32_bf16 v[64:67], v[64:67], v[244:247], v[226:229]
	s_waitcnt lgkmcnt(2)
	v_lshlrev_b32_e32 v220, 16, v136
	v_and_b32_e32 v221, 0xffff0000, v136
	s_waitcnt lgkmcnt(0)
	v_mul_f32_e32 v218, v91, v93
	v_pk_mul_f32 v[220:221], v[218:219], v[220:221] op_sel_hi:[0,1]
	v_cvt_pk_bf16_f32 v136, v220, v221
	v_lshlrev_b32_e32 v220, 16, v137
	v_and_b32_e32 v221, 0xffff0000, v137
	v_pk_mul_f32 v[220:221], v[218:219], v[220:221] op_sel_hi:[0,1]
	v_cvt_pk_bf16_f32 v137, v220, v221
	v_lshlrev_b32_e32 v220, 16, v138
	v_and_b32_e32 v221, 0xffff0000, v138
	v_pk_mul_f32 v[220:221], v[218:219], v[220:221] op_sel_hi:[0,1]
	v_cvt_pk_bf16_f32 v138, v220, v221
	v_lshlrev_b32_e32 v220, 16, v139
	v_and_b32_e32 v221, 0xffff0000, v139
	v_pk_mul_f32 v[218:219], v[218:219], v[220:221] op_sel_hi:[0,1]
	v_cvt_pk_bf16_f32 v139, v218, v219
	ds_write_b128 v85, v[136:139] offset:8704
	ds_read_b128 v[136:139], v85 offset:13056
	ds_read_b32 v91, v186
	ds_read_b32 v93, v187 offset:4
	s_waitcnt lgkmcnt(2)
	v_lshlrev_b32_e32 v220, 16, v136
	v_and_b32_e32 v221, 0xffff0000, v136
	s_waitcnt lgkmcnt(0)
	v_mul_f32_e32 v218, v91, v93
	v_pk_mul_f32 v[220:221], v[218:219], v[220:221] op_sel_hi:[0,1]
	v_cvt_pk_bf16_f32 v136, v220, v221
	v_lshlrev_b32_e32 v220, 16, v137
	v_and_b32_e32 v221, 0xffff0000, v137
	v_pk_mul_f32 v[220:221], v[218:219], v[220:221] op_sel_hi:[0,1]
	v_cvt_pk_bf16_f32 v137, v220, v221
	v_lshlrev_b32_e32 v220, 16, v138
	v_and_b32_e32 v221, 0xffff0000, v138
	v_pk_mul_f32 v[220:221], v[218:219], v[220:221] op_sel_hi:[0,1]
	v_cvt_pk_bf16_f32 v138, v220, v221
	v_lshlrev_b32_e32 v220, 16, v139
	v_and_b32_e32 v221, 0xffff0000, v139
	v_pk_mul_f32 v[218:219], v[218:219], v[220:221] op_sel_hi:[0,1]
	v_cvt_pk_bf16_f32 v139, v218, v219
	ds_write_b128 v85, v[136:139] offset:13056
	ds_read_b128 v[136:139], v85 offset:17408
	ds_read_b32 v91, v188
	ds_read_b32 v93, v189 offset:4
	s_waitcnt lgkmcnt(2)
	v_lshlrev_b32_e32 v220, 16, v136
	v_and_b32_e32 v221, 0xffff0000, v136
	s_waitcnt lgkmcnt(0)
	v_mul_f32_e32 v218, v91, v93
	v_pk_mul_f32 v[220:221], v[218:219], v[220:221] op_sel_hi:[0,1]
	v_cvt_pk_bf16_f32 v136, v220, v221
	v_lshlrev_b32_e32 v220, 16, v137
	v_and_b32_e32 v221, 0xffff0000, v137
	v_pk_mul_f32 v[220:221], v[218:219], v[220:221] op_sel_hi:[0,1]
	v_cvt_pk_bf16_f32 v137, v220, v221
	v_lshlrev_b32_e32 v220, 16, v138
	v_and_b32_e32 v221, 0xffff0000, v138
	v_pk_mul_f32 v[220:221], v[218:219], v[220:221] op_sel_hi:[0,1]
	v_cvt_pk_bf16_f32 v138, v220, v221
	v_lshlrev_b32_e32 v220, 16, v139
	v_and_b32_e32 v221, 0xffff0000, v139
	v_pk_mul_f32 v[218:219], v[218:219], v[220:221] op_sel_hi:[0,1]
	v_cvt_pk_bf16_f32 v139, v218, v219
	ds_write_b128 v85, v[136:139] offset:17408
	ds_read_b128 v[136:139], v85 offset:21760
	ds_read_b32 v91, v190
	ds_read_b32 v93, v191 offset:4
	s_waitcnt lgkmcnt(2)
	v_lshlrev_b32_e32 v220, 16, v136
	v_and_b32_e32 v221, 0xffff0000, v136
	s_waitcnt lgkmcnt(0)
	v_mul_f32_e32 v218, v91, v93
	v_pk_mul_f32 v[220:221], v[218:219], v[220:221] op_sel_hi:[0,1]
	v_cvt_pk_bf16_f32 v136, v220, v221
	v_lshlrev_b32_e32 v220, 16, v137
	v_and_b32_e32 v221, 0xffff0000, v137
	v_pk_mul_f32 v[220:221], v[218:219], v[220:221] op_sel_hi:[0,1]
	v_cvt_pk_bf16_f32 v137, v220, v221
	v_lshlrev_b32_e32 v220, 16, v138
	v_and_b32_e32 v221, 0xffff0000, v138
	v_pk_mul_f32 v[220:221], v[218:219], v[220:221] op_sel_hi:[0,1]
	v_cvt_pk_bf16_f32 v138, v220, v221
	v_lshlrev_b32_e32 v220, 16, v139
	v_and_b32_e32 v221, 0xffff0000, v139
	v_pk_mul_f32 v[218:219], v[218:219], v[220:221] op_sel_hi:[0,1]
	v_cvt_pk_bf16_f32 v139, v218, v219
	ds_write_b128 v85, v[136:139] offset:21760
	ds_read_b128 v[136:139], v85 offset:26112
	ds_read_b32 v91, v192
	ds_read_b32 v93, v193 offset:4
	s_waitcnt lgkmcnt(2)
	v_lshlrev_b32_e32 v220, 16, v136
	v_and_b32_e32 v221, 0xffff0000, v136
	s_waitcnt lgkmcnt(0)
	v_mul_f32_e32 v218, v91, v93
	v_pk_mul_f32 v[220:221], v[218:219], v[220:221] op_sel_hi:[0,1]
	v_cvt_pk_bf16_f32 v136, v220, v221
	v_lshlrev_b32_e32 v220, 16, v137
	v_and_b32_e32 v221, 0xffff0000, v137
	v_pk_mul_f32 v[220:221], v[218:219], v[220:221] op_sel_hi:[0,1]
	v_cvt_pk_bf16_f32 v137, v220, v221
	v_lshlrev_b32_e32 v220, 16, v138
	v_and_b32_e32 v221, 0xffff0000, v138
	v_pk_mul_f32 v[220:221], v[218:219], v[220:221] op_sel_hi:[0,1]
	v_cvt_pk_bf16_f32 v138, v220, v221
	v_lshlrev_b32_e32 v220, 16, v139
	v_and_b32_e32 v221, 0xffff0000, v139
	v_pk_mul_f32 v[218:219], v[218:219], v[220:221] op_sel_hi:[0,1]
	v_cvt_pk_bf16_f32 v139, v218, v219
	ds_write_b128 v85, v[136:139] offset:26112
	ds_read_b128 v[136:139], v85 offset:30464
	ds_read_b32 v91, v194
	ds_read_b32 v93, v195 offset:4
	s_waitcnt lgkmcnt(2)
	v_lshlrev_b32_e32 v220, 16, v136
	v_and_b32_e32 v221, 0xffff0000, v136
	s_waitcnt lgkmcnt(0)
	v_mul_f32_e32 v218, v91, v93
	v_pk_mul_f32 v[220:221], v[218:219], v[220:221] op_sel_hi:[0,1]
	v_cvt_pk_bf16_f32 v136, v220, v221
	v_lshlrev_b32_e32 v220, 16, v137
	v_and_b32_e32 v221, 0xffff0000, v137
	v_pk_mul_f32 v[220:221], v[218:219], v[220:221] op_sel_hi:[0,1]
	v_cvt_pk_bf16_f32 v137, v220, v221
	v_lshlrev_b32_e32 v220, 16, v138
	v_and_b32_e32 v221, 0xffff0000, v138
	v_pk_mul_f32 v[220:221], v[218:219], v[220:221] op_sel_hi:[0,1]
	v_cvt_pk_bf16_f32 v138, v220, v221
	v_lshlrev_b32_e32 v220, 16, v139
	v_and_b32_e32 v221, 0xffff0000, v139
	v_pk_mul_f32 v[218:219], v[218:219], v[220:221] op_sel_hi:[0,1]
	v_cvt_pk_bf16_f32 v139, v218, v219
	ds_write_b128 v85, v[136:139] offset:30464
	v_lshl_add_u64 v[138:139], v[114:115], 0, v[68:69]
	v_add_co_u32_e32 v136, vcc, s37, v138
	s_waitcnt lgkmcnt(0)
	s_nop 0
	v_addc_co_u32_e32 v137, vcc, 0, v139, vcc
	s_barrier
	global_load_dwordx4 v[218:221], v[138:139], off
	global_load_dwordx4 v[222:225], v[136:137], off
	global_load_dwordx4 v[240:243], v[138:139], off offset:64
	global_load_dwordx4 v[244:247], v[136:137], off offset:64
	global_load_dwordx4 v[248:251], v[138:139], off offset:128
	global_load_dwordx4 v[252:255], v[136:137], off offset:128
	ds_read_b128 v[226:229], v204
	s_waitcnt vmcnt(4) lgkmcnt(0)
	v_mfma_f32_16x16x32_bf16 v[4:7], v[226:229], v[218:221], v[4:7]
	s_and_b64 vcc, exec, s[20:21]
	v_mfma_f32_16x16x32_bf16 v[8:11], v[226:229], v[222:225], v[8:11]
	ds_read_b128 v[226:229], v204 offset:4352
	s_waitcnt lgkmcnt(0)
	v_mfma_f32_16x16x32_bf16 v[12:15], v[226:229], v[218:221], v[12:15]
	v_mfma_f32_16x16x32_bf16 v[16:19], v[226:229], v[222:225], v[16:19]
	ds_read_b128 v[226:229], v204 offset:8704
	s_waitcnt lgkmcnt(0)
	v_mfma_f32_16x16x32_bf16 v[20:23], v[226:229], v[218:221], v[20:23]
	v_mfma_f32_16x16x32_bf16 v[24:27], v[226:229], v[222:225], v[24:27]
	ds_read_b128 v[226:229], v204 offset:13056
	s_waitcnt lgkmcnt(0)
	v_mfma_f32_16x16x32_bf16 v[28:31], v[226:229], v[218:221], v[28:31]
	v_mfma_f32_16x16x32_bf16 v[32:35], v[226:229], v[222:225], v[32:35]
	ds_read_b128 v[226:229], v204 offset:17408
	s_waitcnt lgkmcnt(0)
	v_mfma_f32_16x16x32_bf16 v[36:39], v[226:229], v[218:221], v[36:39]
	v_mfma_f32_16x16x32_bf16 v[40:43], v[226:229], v[222:225], v[40:43]
	ds_read_b128 v[226:229], v204 offset:21760
	s_waitcnt lgkmcnt(0)
	v_mfma_f32_16x16x32_bf16 v[44:47], v[226:229], v[218:221], v[44:47]
	v_mfma_f32_16x16x32_bf16 v[48:51], v[226:229], v[222:225], v[48:51]
	ds_read_b128 v[226:229], v204 offset:26112
	s_waitcnt lgkmcnt(0)
	v_mfma_f32_16x16x32_bf16 v[52:55], v[226:229], v[218:221], v[52:55]
	v_mfma_f32_16x16x32_bf16 v[56:59], v[226:229], v[222:225], v[56:59]
	ds_read_b128 v[226:229], v204 offset:30464
	s_waitcnt lgkmcnt(0)
	v_mfma_f32_16x16x32_bf16 v[60:63], v[226:229], v[218:221], v[60:63]
	v_mfma_f32_16x16x32_bf16 v[64:67], v[226:229], v[222:225], v[64:67]
	ds_read_b128 v[226:229], v204 offset:64
	s_waitcnt vmcnt(2) lgkmcnt(0)
	v_mfma_f32_16x16x32_bf16 v[4:7], v[226:229], v[240:243], v[4:7]
	v_mfma_f32_16x16x32_bf16 v[8:11], v[226:229], v[244:247], v[8:11]
	ds_read_b128 v[226:229], v204 offset:4416
	s_waitcnt lgkmcnt(0)
	v_mfma_f32_16x16x32_bf16 v[12:15], v[226:229], v[240:243], v[12:15]
	v_mfma_f32_16x16x32_bf16 v[16:19], v[226:229], v[244:247], v[16:19]
	ds_read_b128 v[226:229], v204 offset:8768
	s_waitcnt lgkmcnt(0)
	v_mfma_f32_16x16x32_bf16 v[20:23], v[226:229], v[240:243], v[20:23]
	v_mfma_f32_16x16x32_bf16 v[24:27], v[226:229], v[244:247], v[24:27]
	ds_read_b128 v[226:229], v204 offset:13120
	s_waitcnt lgkmcnt(0)
	v_mfma_f32_16x16x32_bf16 v[28:31], v[226:229], v[240:243], v[28:31]
	v_mfma_f32_16x16x32_bf16 v[32:35], v[226:229], v[244:247], v[32:35]
	ds_read_b128 v[226:229], v204 offset:17472
	s_waitcnt lgkmcnt(0)
	v_mfma_f32_16x16x32_bf16 v[36:39], v[226:229], v[240:243], v[36:39]
	v_mfma_f32_16x16x32_bf16 v[40:43], v[226:229], v[244:247], v[40:43]
	ds_read_b128 v[226:229], v204 offset:21824
	s_waitcnt lgkmcnt(0)
	v_mfma_f32_16x16x32_bf16 v[44:47], v[226:229], v[240:243], v[44:47]
	v_mfma_f32_16x16x32_bf16 v[48:51], v[226:229], v[244:247], v[48:51]
	ds_read_b128 v[226:229], v204 offset:26176
	s_waitcnt lgkmcnt(0)
	v_mfma_f32_16x16x32_bf16 v[52:55], v[226:229], v[240:243], v[52:55]
	v_mfma_f32_16x16x32_bf16 v[56:59], v[226:229], v[244:247], v[56:59]
	ds_read_b128 v[226:229], v204 offset:30528
	s_waitcnt lgkmcnt(0)
	v_mfma_f32_16x16x32_bf16 v[60:63], v[226:229], v[240:243], v[60:63]
	v_mfma_f32_16x16x32_bf16 v[64:67], v[226:229], v[244:247], v[64:67]
	global_load_dwordx4 v[240:243], v[138:139], off offset:192
	global_load_dwordx4 v[244:247], v[136:137], off offset:192
	ds_read_b128 v[226:229], v204 offset:128
	s_waitcnt vmcnt(2) lgkmcnt(0)
	v_mfma_f32_16x16x32_bf16 v[230:233], v[226:229], v[248:251], v[4:7]
	s_nop 2
	ds_read_b128 v[4:7], v204 offset:4480
	s_waitcnt lgkmcnt(0)
	v_mfma_f32_16x16x32_bf16 v[12:15], v[4:7], v[248:251], v[12:15]
	v_mfma_f32_16x16x32_bf16 v[16:19], v[4:7], v[252:255], v[16:19]
	ds_read_b128 v[4:7], v204 offset:8832
	v_mfma_f32_16x16x32_bf16 v[8:11], v[226:229], v[252:255], v[8:11]
	s_waitcnt lgkmcnt(0)
	v_mfma_f32_16x16x32_bf16 v[20:23], v[4:7], v[248:251], v[20:23]
	v_mfma_f32_16x16x32_bf16 v[226:229], v[4:7], v[252:255], v[24:27]
	ds_read_b128 v[4:7], v204 offset:13184
	s_waitcnt lgkmcnt(0)
	v_mfma_f32_16x16x32_bf16 v[28:31], v[4:7], v[248:251], v[28:31]
	ds_read_b128 v[24:27], v204 offset:30592
	v_mfma_f32_16x16x32_bf16 v[32:35], v[4:7], v[252:255], v[32:35]
	ds_read_b128 v[4:7], v204 offset:17536
	s_waitcnt lgkmcnt(0)
	v_mfma_f32_16x16x32_bf16 v[36:39], v[4:7], v[248:251], v[36:39]
	v_mfma_f32_16x16x32_bf16 v[40:43], v[4:7], v[252:255], v[40:43]
	ds_read_b128 v[4:7], v204 offset:21888
	s_waitcnt lgkmcnt(0)
	v_mfma_f32_16x16x32_bf16 v[44:47], v[4:7], v[248:251], v[44:47]
	v_mfma_f32_16x16x32_bf16 v[48:51], v[4:7], v[252:255], v[48:51]
	ds_read_b128 v[4:7], v204 offset:26240
	s_waitcnt lgkmcnt(0)
	v_mfma_f32_16x16x32_bf16 v[52:55], v[4:7], v[248:251], v[52:55]
	v_mfma_f32_16x16x32_bf16 v[56:59], v[4:7], v[252:255], v[56:59]
	v_mfma_f32_16x16x32_bf16 v[4:7], v[24:27], v[248:251], v[60:63]
	v_mfma_f32_16x16x32_bf16 v[24:27], v[24:27], v[252:255], v[64:67]
	s_nop 1
	ds_read_b128 v[136:139], v204 offset:192
	s_waitcnt vmcnt(0) lgkmcnt(0)
	v_mfma_f32_16x16x32_bf16 v[218:221], v[136:139], v[240:243], v[230:233]
	v_mfma_f32_16x16x32_bf16 v[136:139], v[136:139], v[244:247], v[8:11]
	s_nop 2
	ds_read_b128 v[8:11], v204 offset:4544
	s_waitcnt lgkmcnt(0)
	v_mfma_f32_16x16x32_bf16 v[222:225], v[8:11], v[240:243], v[12:15]
	v_mfma_f32_16x16x32_bf16 v[230:233], v[8:11], v[244:247], v[16:19]
	ds_read_b128 v[8:11], v204 offset:8896
	s_waitcnt lgkmcnt(0)
	v_mfma_f32_16x16x32_bf16 v[234:237], v[8:11], v[240:243], v[20:23]
	v_mfma_f32_16x16x32_bf16 v[226:229], v[8:11], v[244:247], v[226:229]
	ds_read_b128 v[8:11], v204 offset:13248
	s_waitcnt lgkmcnt(0)
	v_mfma_f32_16x16x32_bf16 v[28:31], v[8:11], v[240:243], v[28:31]
	v_mfma_f32_16x16x32_bf16 v[32:35], v[8:11], v[244:247], v[32:35]
	ds_read_b128 v[8:11], v204 offset:17600
	s_waitcnt lgkmcnt(0)
	v_mfma_f32_16x16x32_bf16 v[36:39], v[8:11], v[240:243], v[36:39]
	v_mfma_f32_16x16x32_bf16 v[40:43], v[8:11], v[244:247], v[40:43]
	ds_read_b128 v[8:11], v204 offset:21952
	s_waitcnt lgkmcnt(0)
	v_mfma_f32_16x16x32_bf16 v[44:47], v[8:11], v[240:243], v[44:47]
	v_mfma_f32_16x16x32_bf16 v[20:23], v[8:11], v[244:247], v[48:51]
	ds_read_b128 v[8:11], v204 offset:26304
	s_nop 1
	ds_read_b128 v[48:51], v204 offset:30656
	s_waitcnt lgkmcnt(1)
	v_mfma_f32_16x16x32_bf16 v[16:19], v[8:11], v[240:243], v[52:55]
	s_waitcnt lgkmcnt(0)
	s_barrier
	v_mfma_f32_16x16x32_bf16 v[12:15], v[8:11], v[244:247], v[56:59]
	v_cvt_pk_bf16_f32 v20, v20, s0
	s_nop 3
	v_cvt_pk_bf16_f32 v16, v16, s0
	ds_write_b16 v205, v20 offset:21792
	v_mfma_f32_16x16x32_bf16 v[8:11], v[48:51], v[240:243], v[4:7]
	v_cvt_pk_bf16_f32 v20, v21, s0
	v_cvt_pk_bf16_f32 v12, v12, s0
	ds_write_b16 v205, v16 offset:26112
	v_mfma_f32_16x16x32_bf16 v[4:7], v[48:51], v[244:247], v[24:27]
	v_cvt_pk_bf16_f32 v16, v17, s0
	s_nop 2
	v_cvt_pk_bf16_f32 v8, v8, s0
	ds_write_b16 v205, v12 offset:26144
	v_cvt_pk_bf16_f32 v24, v218, s0
	ds_write_b16 v205, v24
	v_cvt_pk_bf16_f32 v24, v219, s0
	ds_write_b16 v205, v24 offset:272
	v_cvt_pk_bf16_f32 v24, v220, s0
	ds_write_b16 v205, v24 offset:544
	v_cvt_pk_bf16_f32 v24, v221, s0
	ds_write_b16 v205, v24 offset:816
	v_cvt_pk_bf16_f32 v24, v136, s0
	ds_write_b16 v205, v24 offset:32
	v_cvt_pk_bf16_f32 v24, v137, s0
	ds_write_b16 v205, v24 offset:304
	v_cvt_pk_bf16_f32 v24, v138, s0
	ds_write_b16 v205, v24 offset:576
	v_cvt_pk_bf16_f32 v24, v139, s0
	ds_write_b16 v205, v24 offset:848
	v_cvt_pk_bf16_f32 v24, v222, s0
	ds_write_b16 v205, v24 offset:4352
	v_cvt_pk_bf16_f32 v24, v223, s0
	ds_write_b16 v205, v24 offset:4624
	v_cvt_pk_bf16_f32 v24, v224, s0
	ds_write_b16 v205, v24 offset:4896
	v_cvt_pk_bf16_f32 v24, v225, s0
	ds_write_b16 v205, v24 offset:5168
	v_cvt_pk_bf16_f32 v24, v230, s0
	ds_write_b16 v205, v24 offset:4384
	v_cvt_pk_bf16_f32 v24, v231, s0
	ds_write_b16 v205, v24 offset:4656
	v_cvt_pk_bf16_f32 v24, v232, s0
	ds_write_b16 v205, v24 offset:4928
	v_cvt_pk_bf16_f32 v24, v233, s0
	ds_write_b16 v205, v24 offset:5200
	v_cvt_pk_bf16_f32 v24, v234, s0
	ds_write_b16 v205, v24 offset:8704
	v_cvt_pk_bf16_f32 v24, v235, s0
	ds_write_b16 v205, v24 offset:8976
	v_cvt_pk_bf16_f32 v24, v236, s0
	ds_write_b16 v205, v24 offset:9248
	v_cvt_pk_bf16_f32 v24, v237, s0
	ds_write_b16 v205, v24 offset:9520
	v_cvt_pk_bf16_f32 v24, v226, s0
	ds_write_b16 v205, v24 offset:8736
	v_cvt_pk_bf16_f32 v24, v227, s0
	ds_write_b16 v205, v24 offset:9008
	v_cvt_pk_bf16_f32 v24, v228, s0
	ds_write_b16 v205, v24 offset:9280
	v_cvt_pk_bf16_f32 v24, v229, s0
	ds_write_b16 v205, v24 offset:9552
	v_cvt_pk_bf16_f32 v24, v28, s0
	ds_write_b16 v205, v24 offset:13056
	v_cvt_pk_bf16_f32 v24, v29, s0
	ds_write_b16 v205, v24 offset:13328
	v_cvt_pk_bf16_f32 v24, v30, s0
	ds_write_b16 v205, v24 offset:13600
	v_cvt_pk_bf16_f32 v24, v31, s0
	ds_write_b16 v205, v24 offset:13872
	v_cvt_pk_bf16_f32 v24, v32, s0
	ds_write_b16 v205, v24 offset:13088
	v_cvt_pk_bf16_f32 v24, v33, s0
	ds_write_b16 v205, v24 offset:13360
	v_cvt_pk_bf16_f32 v24, v34, s0
	ds_write_b16 v205, v24 offset:13632
	v_cvt_pk_bf16_f32 v24, v35, s0
	ds_write_b16 v205, v24 offset:13904
	v_cvt_pk_bf16_f32 v24, v36, s0
	ds_write_b16 v205, v24 offset:17408
	v_cvt_pk_bf16_f32 v24, v37, s0
	ds_write_b16 v205, v24 offset:17680
	v_cvt_pk_bf16_f32 v24, v38, s0
	ds_write_b16 v205, v24 offset:17952
	v_cvt_pk_bf16_f32 v24, v39, s0
	ds_write_b16 v205, v24 offset:18224
	v_cvt_pk_bf16_f32 v24, v40, s0
	ds_write_b16 v205, v24 offset:17440
	v_cvt_pk_bf16_f32 v24, v41, s0
	ds_write_b16 v205, v24 offset:17712
	v_cvt_pk_bf16_f32 v24, v42, s0
	ds_write_b16 v205, v24 offset:17984
	v_cvt_pk_bf16_f32 v24, v43, s0
	ds_write_b16 v205, v24 offset:18256
	v_cvt_pk_bf16_f32 v24, v44, s0
	v_cvt_pk_bf16_f32 v4, v4, s0
	ds_write_b16 v205, v24 offset:21760
	v_cvt_pk_bf16_f32 v24, v45, s0
	v_cvt_pk_bf16_f32 v12, v13, s0
	ds_write_b16 v205, v8 offset:30464
	v_cvt_pk_bf16_f32 v8, v9, s0
	ds_write_b16 v205, v4 offset:30496
	v_cvt_pk_bf16_f32 v4, v5, s0
	ds_write_b16 v205, v24 offset:22032
	v_cvt_pk_bf16_f32 v24, v46, s0
	ds_write_b16 v205, v20 offset:22064
	v_cvt_pk_bf16_f32 v20, v22, s0
	ds_write_b16 v205, v16 offset:26384
	v_cvt_pk_bf16_f32 v16, v18, s0
	ds_write_b16 v205, v12 offset:26416
	v_cvt_pk_bf16_f32 v12, v14, s0
	ds_write_b16 v205, v8 offset:30736
	v_cvt_pk_bf16_f32 v8, v10, s0
	ds_write_b16 v205, v4 offset:30768
	v_cvt_pk_bf16_f32 v4, v6, s0
	ds_write_b16 v205, v24 offset:22304
	v_cvt_pk_bf16_f32 v24, v47, s0
	ds_write_b16 v205, v20 offset:22336
	v_cvt_pk_bf16_f32 v20, v23, s0
	ds_write_b16 v205, v16 offset:26656
	v_cvt_pk_bf16_f32 v16, v19, s0
	ds_write_b16 v205, v12 offset:26688
	v_cvt_pk_bf16_f32 v12, v15, s0
	ds_write_b16 v205, v8 offset:31008
	v_cvt_pk_bf16_f32 v8, v11, s0
	ds_write_b16 v205, v4 offset:31040
	v_cvt_pk_bf16_f32 v4, v7, s0
	ds_write_b16 v205, v24 offset:22576
	ds_write_b16 v205, v20 offset:22608
	ds_write_b16 v205, v16 offset:26928
	ds_write_b16 v205, v12 offset:26960
	ds_write_b16 v205, v8 offset:31280
	ds_write_b16 v205, v4 offset:31312
	s_waitcnt lgkmcnt(0)
	s_barrier
	ds_read_b128 v[4:7], v85
	v_lshl_add_u64 v[8:9], s[24:25], 1, v[116:117]
	v_lshl_add_u64 v[10:11], v[8:9], 0, v[118:119]
	s_movk_i32 s24, 0x80
	s_waitcnt lgkmcnt(0)
	flat_store_dwordx4 v[10:11], v[4:7]
	ds_read_b128 v[4:7], v85 offset:4352
	v_lshl_add_u64 v[10:11], v[8:9], 0, v[120:121]
	s_waitcnt lgkmcnt(0)
	flat_store_dwordx4 v[10:11], v[4:7]
	ds_read_b128 v[4:7], v85 offset:8704
	v_lshl_add_u64 v[10:11], v[8:9], 0, v[122:123]
	s_waitcnt lgkmcnt(0)
	flat_store_dwordx4 v[10:11], v[4:7]
	ds_read_b128 v[4:7], v85 offset:13056
	v_lshl_add_u64 v[10:11], v[8:9], 0, v[124:125]
	s_waitcnt lgkmcnt(0)
	flat_store_dwordx4 v[10:11], v[4:7]
	ds_read_b128 v[4:7], v85 offset:17408
	v_lshl_add_u64 v[10:11], v[8:9], 0, v[126:127]
	s_waitcnt lgkmcnt(0)
	flat_store_dwordx4 v[10:11], v[4:7]
	ds_read_b128 v[4:7], v85 offset:21760
	v_lshl_add_u64 v[10:11], v[8:9], 0, v[128:129]
	s_waitcnt lgkmcnt(0)
	flat_store_dwordx4 v[10:11], v[4:7]
	ds_read_b128 v[4:7], v85 offset:26112
	v_lshl_add_u64 v[10:11], v[8:9], 0, v[130:131]
	v_lshl_add_u64 v[8:9], v[8:9], 0, v[134:135]
	s_waitcnt lgkmcnt(0)
	flat_store_dwordx4 v[10:11], v[4:7]
	ds_read_b128 v[4:7], v85 offset:30464
	s_waitcnt lgkmcnt(0)
	flat_store_dwordx4 v[8:9], v[4:7]
	s_waitcnt lgkmcnt(0)
	s_barrier
	s_cbranch_vccnz .LBB0_743
